# leading half runs its w_in/GU epilogue before its alignment barrier (overlaps trailing half's last MFMA phase)
# baseline (speedup 1.0000x reference)
.LBB0_166:
.LBB0_168:
	s_waitcnt vmcnt(8)
	v_pk_mul_f32 v[126:127], v[142:143], v[126:127] op_sel_hi:[0,1]
	v_pk_mul_f32 v[124:125], v[142:143], v[124:125] op_sel_hi:[0,1]
	v_pk_mul_f32 v[156:157], v[142:143], v[122:123] op_sel_hi:[0,1]
	v_pk_mul_f32 v[122:123], v[142:143], v[120:121] op_sel_hi:[0,1]
	v_cvt_pk_bf16_f32 v120, v124, v125
	v_cvt_pk_bf16_f32 v121, v126, v127
	v_cvt_pk_bf16_f32 v122, v122, v123
	v_cvt_pk_bf16_f32 v123, v156, v157
	ds_write_b128 v155, v[120:123]
	v_pk_mul_f32 v[118:119], v[142:143], v[118:119] op_sel_hi:[0,1]
	v_pk_mul_f32 v[116:117], v[142:143], v[116:117] op_sel_hi:[0,1]
	v_pk_mul_f32 v[120:121], v[142:143], v[114:115] op_sel_hi:[0,1]
	v_pk_mul_f32 v[114:115], v[142:143], v[112:113] op_sel_hi:[0,1]
	v_cvt_pk_bf16_f32 v112, v116, v117
	v_cvt_pk_bf16_f32 v113, v118, v119
	v_cvt_pk_bf16_f32 v114, v114, v115
	v_cvt_pk_bf16_f32 v115, v120, v121
	ds_write_b128 v155, v[112:115] offset:64
	v_add_u32_e32 v124, s3, v145
	v_mov_b64_e32 v[112:113], s[50:51]
	v_mad_i64_i32 v[122:123], s[38:39], v124, s6, v[112:113]
	s_lshl_b32 s38, s2, 8
	s_waitcnt lgkmcnt(0)
	s_ashr_i32 s39, s38, 31
	ds_read_b128 v[114:117], v158
	ds_read_b128 v[118:121], v158 offset:1152
	s_lshl_b64 s[38:39], s[38:39], 1
	v_lshl_add_u64 v[122:123], v[122:123], 0, s[38:39]
	v_lshl_add_u64 v[122:123], v[122:123], 0, s[0:1]
	v_lshl_add_u64 v[122:123], v[122:123], 0, v[208:209]
	s_movk_i32 s27, 0x7000
	s_waitcnt lgkmcnt(1)
	global_store_dwordx4 v[122:123], v[114:117], off sc1 nt
	v_pk_mul_f32 v[110:111], v[144:145], v[110:111] op_sel_hi:[0,1]
	v_pk_mul_f32 v[108:109], v[144:145], v[108:109] op_sel_hi:[0,1]
	v_add_co_u32_e32 v114, vcc, s27, v122
	v_pk_mul_f32 v[102:103], v[144:145], v[102:103] op_sel_hi:[0,1]
	s_nop 0
	v_addc_co_u32_e32 v115, vcc, 0, v123, vcc
	s_waitcnt lgkmcnt(0)
	global_store_dwordx4 v[114:115], v[118:121], off sc1 nt
	s_waitcnt lgkmcnt(0)
	v_pk_mul_f32 v[114:115], v[144:145], v[106:107] op_sel_hi:[0,1]
	v_pk_mul_f32 v[106:107], v[144:145], v[104:105] op_sel_hi:[0,1]
	v_cvt_pk_bf16_f32 v104, v108, v109
	v_cvt_pk_bf16_f32 v105, v110, v111
	v_cvt_pk_bf16_f32 v106, v106, v107
	v_cvt_pk_bf16_f32 v107, v114, v115
	ds_write_b128 v155, v[104:107]
	v_pk_mul_f32 v[104:105], v[144:145], v[98:99] op_sel_hi:[0,1]
	v_pk_mul_f32 v[98:99], v[144:145], v[96:97] op_sel_hi:[0,1]
	v_pk_mul_f32 v[100:101], v[144:145], v[100:101] op_sel_hi:[0,1]
	v_cvt_pk_bf16_f32 v96, v100, v101
	v_cvt_pk_bf16_f32 v97, v102, v103
	v_cvt_pk_bf16_f32 v98, v98, v99
	v_cvt_pk_bf16_f32 v99, v104, v105
	ds_write_b128 v155, v[96:99] offset:64
	s_waitcnt lgkmcnt(0)
	v_add_u32_e32 v104, s3, v147
	ds_read_b128 v[96:99], v158
	ds_read_b128 v[100:103], v158 offset:1152
	v_mad_i64_i32 v[104:105], s[40:41], v104, s6, v[112:113]
	v_lshl_add_u64 v[104:105], v[104:105], 0, s[38:39]
	v_lshl_add_u64 v[104:105], v[104:105], 0, s[0:1]
	v_lshl_add_u64 v[104:105], v[104:105], 0, v[208:209]
	s_waitcnt lgkmcnt(1)
	global_store_dwordx4 v[104:105], v[96:99], off sc1 nt
	v_pk_mul_f32 v[94:95], v[146:147], v[94:95] op_sel_hi:[0,1]
	v_pk_mul_f32 v[92:93], v[146:147], v[92:93] op_sel_hi:[0,1]
	v_add_co_u32_e32 v96, vcc, s27, v104
	v_pk_mul_f32 v[86:87], v[146:147], v[86:87] op_sel_hi:[0,1]
	s_nop 0
	v_addc_co_u32_e32 v97, vcc, 0, v105, vcc
	s_waitcnt lgkmcnt(0)
	global_store_dwordx4 v[96:97], v[100:103], off sc1 nt
	s_waitcnt lgkmcnt(0)
	v_pk_mul_f32 v[96:97], v[146:147], v[90:91] op_sel_hi:[0,1]
	v_pk_mul_f32 v[90:91], v[146:147], v[88:89] op_sel_hi:[0,1]
	v_cvt_pk_bf16_f32 v88, v92, v93
	v_cvt_pk_bf16_f32 v89, v94, v95
	v_cvt_pk_bf16_f32 v90, v90, v91
	v_cvt_pk_bf16_f32 v91, v96, v97
	ds_write_b128 v155, v[88:91]
	v_pk_mul_f32 v[88:89], v[146:147], v[82:83] op_sel_hi:[0,1]
	v_pk_mul_f32 v[82:83], v[146:147], v[80:81] op_sel_hi:[0,1]
	v_pk_mul_f32 v[84:85], v[146:147], v[84:85] op_sel_hi:[0,1]
	v_cvt_pk_bf16_f32 v80, v84, v85
	v_cvt_pk_bf16_f32 v81, v86, v87
	v_cvt_pk_bf16_f32 v82, v82, v83
	v_cvt_pk_bf16_f32 v83, v88, v89
	ds_write_b128 v155, v[80:83] offset:64
	s_waitcnt lgkmcnt(0)
	v_add_u32_e32 v88, s3, v149
	ds_read_b128 v[80:83], v158
	ds_read_b128 v[84:87], v158 offset:1152
	v_mad_i64_i32 v[88:89], s[40:41], v88, s6, v[112:113]
	v_lshl_add_u64 v[88:89], v[88:89], 0, s[38:39]
	v_lshl_add_u64 v[88:89], v[88:89], 0, s[0:1]
	v_lshl_add_u64 v[88:89], v[88:89], 0, v[208:209]
	s_waitcnt lgkmcnt(1)
	global_store_dwordx4 v[88:89], v[80:83], off sc1 nt
	v_pk_mul_f32 v[78:79], v[148:149], v[78:79] op_sel_hi:[0,1]
	v_pk_mul_f32 v[76:77], v[148:149], v[76:77] op_sel_hi:[0,1]
	v_add_co_u32_e32 v80, vcc, s27, v88
	v_pk_mul_f32 v[70:71], v[148:149], v[70:71] op_sel_hi:[0,1]
	s_nop 0
	v_addc_co_u32_e32 v81, vcc, 0, v89, vcc
	s_waitcnt lgkmcnt(0)
	global_store_dwordx4 v[80:81], v[84:87], off sc1 nt
	s_waitcnt lgkmcnt(0)
	v_pk_mul_f32 v[80:81], v[148:149], v[74:75] op_sel_hi:[0,1]
	v_pk_mul_f32 v[74:75], v[148:149], v[72:73] op_sel_hi:[0,1]
	v_cvt_pk_bf16_f32 v72, v76, v77
	v_cvt_pk_bf16_f32 v73, v78, v79
	v_cvt_pk_bf16_f32 v74, v74, v75
	v_cvt_pk_bf16_f32 v75, v80, v81
	ds_write_b128 v155, v[72:75]
	v_pk_mul_f32 v[72:73], v[148:149], v[66:67] op_sel_hi:[0,1]
	v_pk_mul_f32 v[66:67], v[148:149], v[64:65] op_sel_hi:[0,1]
	v_pk_mul_f32 v[68:69], v[148:149], v[68:69] op_sel_hi:[0,1]
	v_cvt_pk_bf16_f32 v64, v68, v69
	v_cvt_pk_bf16_f32 v65, v70, v71
	v_cvt_pk_bf16_f32 v66, v66, v67
	v_cvt_pk_bf16_f32 v67, v72, v73
	ds_write_b128 v155, v[64:67] offset:64
	s_waitcnt lgkmcnt(0)
	v_add_u32_e32 v72, s3, v151
	ds_read_b128 v[64:67], v158
	ds_read_b128 v[68:71], v158 offset:1152
	v_mad_i64_i32 v[72:73], s[2:3], v72, s6, v[112:113]
	v_lshl_add_u64 v[72:73], v[72:73], 0, s[38:39]
	v_lshl_add_u64 v[72:73], v[72:73], 0, s[0:1]
	v_lshl_add_u64 v[72:73], v[72:73], 0, v[208:209]
	s_waitcnt lgkmcnt(1)
	global_store_dwordx4 v[72:73], v[64:67], off sc1 nt
	v_pk_mul_f32 v[62:63], v[150:151], v[62:63] op_sel_hi:[0,1]
	v_pk_mul_f32 v[60:61], v[150:151], v[60:61] op_sel_hi:[0,1]
	v_add_co_u32_e32 v64, vcc, s27, v72
	v_pk_mul_f32 v[54:55], v[150:151], v[54:55] op_sel_hi:[0,1]
	s_nop 0
	v_addc_co_u32_e32 v65, vcc, 0, v73, vcc
	s_waitcnt lgkmcnt(0)
	global_store_dwordx4 v[64:65], v[68:71], off sc1 nt
	s_waitcnt lgkmcnt(0)
	v_pk_mul_f32 v[64:65], v[150:151], v[58:59] op_sel_hi:[0,1]
	v_pk_mul_f32 v[58:59], v[150:151], v[56:57] op_sel_hi:[0,1]
	v_cvt_pk_bf16_f32 v56, v60, v61
	v_cvt_pk_bf16_f32 v57, v62, v63
	v_cvt_pk_bf16_f32 v58, v58, v59
	v_cvt_pk_bf16_f32 v59, v64, v65
	ds_write_b128 v155, v[56:59]
	v_pk_mul_f32 v[56:57], v[150:151], v[50:51] op_sel_hi:[0,1]
	v_pk_mul_f32 v[50:51], v[150:151], v[48:49] op_sel_hi:[0,1]
	v_pk_mul_f32 v[52:53], v[150:151], v[52:53] op_sel_hi:[0,1]
	v_cvt_pk_bf16_f32 v48, v52, v53
	v_cvt_pk_bf16_f32 v49, v54, v55
	v_cvt_pk_bf16_f32 v50, v50, v51
	v_cvt_pk_bf16_f32 v51, v56, v57
	ds_write_b128 v155, v[48:51] offset:64
	s_waitcnt lgkmcnt(0)
	v_add_u32_e32 v56, 0x80, v124
	ds_read_b128 v[48:51], v158
	ds_read_b128 v[52:55], v158 offset:1152
	v_mad_i64_i32 v[56:57], s[2:3], v56, s6, v[112:113]
	v_lshl_add_u64 v[56:57], v[56:57], 0, s[38:39]
	v_lshl_add_u64 v[56:57], v[56:57], 0, s[0:1]
	v_lshl_add_u64 v[56:57], v[56:57], 0, v[208:209]
	s_waitcnt lgkmcnt(1)
	global_store_dwordx4 v[56:57], v[48:51], off sc1 nt
	v_pk_mul_f32 v[46:47], v[152:153], v[46:47] op_sel_hi:[0,1]
	v_pk_mul_f32 v[44:45], v[152:153], v[44:45] op_sel_hi:[0,1]
	v_add_co_u32_e32 v48, vcc, s27, v56
	v_pk_mul_f32 v[38:39], v[152:153], v[38:39] op_sel_hi:[0,1]
	s_nop 0
	v_addc_co_u32_e32 v49, vcc, 0, v57, vcc
	s_waitcnt lgkmcnt(0)
	global_store_dwordx4 v[48:49], v[52:55], off sc1 nt
	s_waitcnt lgkmcnt(0)
	v_pk_mul_f32 v[48:49], v[152:153], v[42:43] op_sel_hi:[0,1]
	v_pk_mul_f32 v[42:43], v[152:153], v[40:41] op_sel_hi:[0,1]
	v_cvt_pk_bf16_f32 v40, v44, v45
	v_cvt_pk_bf16_f32 v41, v46, v47
	v_cvt_pk_bf16_f32 v42, v42, v43
	v_cvt_pk_bf16_f32 v43, v48, v49
	ds_write_b128 v155, v[40:43]
	v_pk_mul_f32 v[40:41], v[152:153], v[34:35] op_sel_hi:[0,1]
	v_pk_mul_f32 v[34:35], v[152:153], v[32:33] op_sel_hi:[0,1]
	v_pk_mul_f32 v[36:37], v[152:153], v[36:37] op_sel_hi:[0,1]
	v_cvt_pk_bf16_f32 v32, v36, v37
	v_cvt_pk_bf16_f32 v33, v38, v39
	v_cvt_pk_bf16_f32 v34, v34, v35
	v_cvt_pk_bf16_f32 v35, v40, v41
	ds_write_b128 v155, v[32:35] offset:64
	s_waitcnt lgkmcnt(0)
	v_add_u32_e32 v40, 0x90, v124
	ds_read_b128 v[32:35], v158
	ds_read_b128 v[36:39], v158 offset:1152
	v_mad_i64_i32 v[40:41], s[2:3], v40, s6, v[112:113]
	v_lshl_add_u64 v[40:41], v[40:41], 0, s[38:39]
	v_lshl_add_u64 v[40:41], v[40:41], 0, s[0:1]
	v_lshl_add_u64 v[40:41], v[40:41], 0, v[208:209]
	s_waitcnt lgkmcnt(1)
	global_store_dwordx4 v[40:41], v[32:35], off sc1 nt
	v_pk_mul_f32 v[30:31], v[154:155], v[30:31] op_sel_hi:[0,1]
	v_pk_mul_f32 v[28:29], v[154:155], v[28:29] op_sel_hi:[0,1]
	v_add_co_u32_e32 v32, vcc, s27, v40
	v_pk_mul_f32 v[22:23], v[154:155], v[22:23] op_sel_hi:[0,1]
	s_nop 0
	v_addc_co_u32_e32 v33, vcc, 0, v41, vcc
	s_waitcnt lgkmcnt(0)
	global_store_dwordx4 v[32:33], v[36:39], off sc1 nt
	s_waitcnt lgkmcnt(0)
	v_pk_mul_f32 v[32:33], v[154:155], v[26:27] op_sel_hi:[0,1]
	v_pk_mul_f32 v[26:27], v[154:155], v[24:25] op_sel_hi:[0,1]
	v_cvt_pk_bf16_f32 v24, v28, v29
	v_cvt_pk_bf16_f32 v25, v30, v31
	v_cvt_pk_bf16_f32 v26, v26, v27
	v_cvt_pk_bf16_f32 v27, v32, v33
	ds_write_b128 v155, v[24:27]
	v_pk_mul_f32 v[24:25], v[154:155], v[18:19] op_sel_hi:[0,1]
	v_pk_mul_f32 v[18:19], v[154:155], v[16:17] op_sel_hi:[0,1]
	v_pk_mul_f32 v[20:21], v[154:155], v[20:21] op_sel_hi:[0,1]
	v_cvt_pk_bf16_f32 v16, v20, v21
	v_cvt_pk_bf16_f32 v17, v22, v23
	v_cvt_pk_bf16_f32 v18, v18, v19
	v_cvt_pk_bf16_f32 v19, v24, v25
	ds_write_b128 v155, v[16:19] offset:64
	s_waitcnt lgkmcnt(0)
	v_add_u32_e32 v24, 0xa0, v124
	ds_read_b128 v[16:19], v158
	ds_read_b128 v[20:23], v158 offset:1152
	v_mad_i64_i32 v[24:25], s[2:3], v24, s6, v[112:113]
	v_lshl_add_u64 v[24:25], v[24:25], 0, s[38:39]
	v_lshl_add_u64 v[24:25], v[24:25], 0, s[0:1]
	v_lshl_add_u64 v[24:25], v[24:25], 0, v[208:209]
	s_waitcnt lgkmcnt(1)
	global_store_dwordx4 v[24:25], v[16:19], off sc1 nt
	v_pk_mul_f32 v[14:15], v[140:141], v[14:15] op_sel_hi:[0,1]
	v_pk_mul_f32 v[12:13], v[140:141], v[12:13] op_sel_hi:[0,1]
	v_add_co_u32_e32 v16, vcc, s27, v24
	v_pk_mul_f32 v[6:7], v[140:141], v[6:7] op_sel_hi:[0,1]
	s_nop 0
	v_addc_co_u32_e32 v17, vcc, 0, v25, vcc
	s_waitcnt lgkmcnt(0)
	global_store_dwordx4 v[16:17], v[20:23], off sc1 nt
	s_waitcnt lgkmcnt(0)
	v_pk_mul_f32 v[16:17], v[140:141], v[10:11] op_sel_hi:[0,1]
	v_pk_mul_f32 v[10:11], v[140:141], v[8:9] op_sel_hi:[0,1]
	v_cvt_pk_bf16_f32 v8, v12, v13
	v_cvt_pk_bf16_f32 v9, v14, v15
	v_cvt_pk_bf16_f32 v10, v10, v11
	v_cvt_pk_bf16_f32 v11, v16, v17
	ds_write_b128 v155, v[8:11]
	v_pk_mul_f32 v[8:9], v[140:141], v[2:3] op_sel_hi:[0,1]
	v_pk_mul_f32 v[2:3], v[140:141], v[0:1] op_sel_hi:[0,1]
	v_pk_mul_f32 v[4:5], v[140:141], v[4:5] op_sel_hi:[0,1]
	v_cvt_pk_bf16_f32 v0, v4, v5
	v_cvt_pk_bf16_f32 v1, v6, v7
	v_cvt_pk_bf16_f32 v2, v2, v3
	v_cvt_pk_bf16_f32 v3, v8, v9
	ds_write_b128 v155, v[0:3] offset:64
	s_waitcnt lgkmcnt(0)
	v_add_u32_e32 v8, 0xb0, v124
	ds_read_b128 v[0:3], v158
	ds_read_b128 v[4:7], v158 offset:1152
	v_mad_i64_i32 v[8:9], s[2:3], v8, s6, v[112:113]
	v_lshl_add_u64 v[8:9], v[8:9], 0, s[38:39]
	v_lshl_add_u64 v[8:9], v[8:9], 0, s[0:1]
	v_lshl_add_u64 v[8:9], v[8:9], 0, v[208:209]
	s_waitcnt lgkmcnt(1)
	global_store_dwordx4 v[8:9], v[0:3], off sc1 nt
	s_movk_i32 s59, 0x7000
	s_mov_b64 s[2:3], -1
	v_add_co_u32_e32 v0, vcc, 0x7000, v8
	s_nop 1
	v_addc_co_u32_e32 v1, vcc, 0, v9, vcc
	s_waitcnt lgkmcnt(0)
	global_store_dwordx4 v[0:1], v[4:7], off sc1 nt
	s_waitcnt lgkmcnt(0)
	s_andn2_b64 vcc, exec, s[36:37]
	s_cmp_eq_u64 s[24:25], 0
	s_cbranch_scc1 .Lwin_lhalf_done
	s_barrier
.Lwin_lhalf_done:
	s_cbranch_vccnz .LBB0_159
	s_andn2_b64 vcc, exec, s[22:23]
	s_cbranch_vccnz .LBB0_158
	s_barrier
	s_branch .LBB0_158

.LBB0_574:
.LBB0_576:
	s_waitcnt vmcnt(8)
	v_mul_f32_e32 v170, 0xbfb8aa3b, v168
	v_pk_mul_f32 v[176:177], v[170:171], v[116:117] op_sel_hi:[0,1]
	v_exp_f32_e32 v169, v176
	v_pk_mul_f32 v[120:121], v[124:125], v[120:121]
	v_pk_mul_f32 v[124:125], v[170:171], v[124:125] op_sel_hi:[0,1]
	v_pk_mul_f32 v[122:123], v[126:127], v[122:123]
	v_pk_mul_f32 v[174:175], v[170:171], v[118:119] op_sel_hi:[0,1]
	v_pk_mul_f32 v[126:127], v[170:171], v[126:127] op_sel_hi:[0,1]
	v_exp_f32_e32 v170, v124
	v_add_f32_e32 v124, 1.0, v169
	v_exp_f32_e32 v169, v177
	v_exp_f32_e32 v171, v125
	v_exp_f32_e32 v173, v126
	s_mul_i32 s3, s38, 22
	v_add_f32_e32 v125, 1.0, v169
	v_exp_f32_e32 v169, v174
	s_add_i32 s2, s3, s2
	s_ashr_i32 s3, s2, 31
	v_rcp_f32_e32 v124, v124
	v_add_f32_e32 v126, 1.0, v169
	v_exp_f32_e32 v169, v175
	v_exp_f32_e32 v175, v127
	v_add_f32_e32 v170, 1.0, v170
	v_rcp_f32_e32 v125, v125
	v_add_f32_e32 v127, 1.0, v169
	v_add_f32_e32 v171, 1.0, v171
	v_rcp_f32_e32 v126, v126
	v_rcp_f32_e32 v127, v127
	s_lshl_b64 s[2:3], s[2:3], 16
	v_rcp_f32_e32 v170, v170
	v_rcp_f32_e32 v171, v171
	v_add_f32_e32 v173, 1.0, v173
	v_add_f32_e32 v169, 1.0, v175
	s_add_u32 s38, s50, s2
	v_mul_f32_e32 v172, v168, v168
	v_rcp_f32_e32 v174, v173
	v_rcp_f32_e32 v175, v169
	v_pk_mul_f32 v[114:115], v[118:119], v[114:115]
	v_pk_mul_f32 v[112:113], v[116:117], v[112:113]
	s_addc_u32 s39, s51, s3
	v_pk_mul_f32 v[112:113], v[172:173], v[112:113] op_sel_hi:[0,1]
	v_pk_mul_f32 v[114:115], v[172:173], v[114:115] op_sel_hi:[0,1]
	v_lshl_add_u64 v[156:157], s[38:39], 0, v[136:137]
	v_pk_mul_f32 v[116:117], v[172:173], v[120:121] op_sel_hi:[0,1]
	v_pk_mul_f32 v[114:115], v[126:127], v[114:115]
	v_pk_mul_f32 v[112:113], v[124:125], v[112:113]
	v_lshl_add_u64 v[156:157], v[156:157], 0, v[208:209]
	v_pk_mul_f32 v[118:119], v[172:173], v[122:123] op_sel_hi:[0,1]
	v_pk_mul_f32 v[116:117], v[170:171], v[116:117]
	v_cvt_pk_bf16_f32 v112, v112, v113
	v_cvt_pk_bf16_f32 v113, v114, v115
	v_pk_mul_f32 v[118:119], v[174:175], v[118:119]
	v_cvt_pk_bf16_f32 v114, v116, v117
	v_pk_mul_f32 v[104:105], v[108:109], v[104:105]
	v_cvt_pk_bf16_f32 v115, v118, v119
	global_store_dwordx4 v[156:157], v[112:115], off sc1 nt
	v_pk_mul_f32 v[106:107], v[110:111], v[106:107]
	v_mul_f32_e32 v116, v167, v167
	v_mul_f32_e32 v114, 0xbfb8aa3b, v167
	v_pk_mul_f32 v[120:121], v[114:115], v[100:101] op_sel_hi:[0,1]
	v_pk_mul_f32 v[118:119], v[114:115], v[102:103] op_sel_hi:[0,1]
	v_exp_f32_e32 v115, v120
	v_exp_f32_e32 v118, v118
	v_exp_f32_e32 v119, v119
	v_pk_mul_f32 v[98:99], v[102:103], v[98:99]
	v_pk_mul_f32 v[108:109], v[114:115], v[108:109] op_sel_hi:[0,1]
	v_pk_mul_f32 v[110:111], v[114:115], v[110:111] op_sel_hi:[0,1]
	v_exp_f32_e32 v114, v108
	v_add_f32_e32 v108, 1.0, v115
	v_exp_f32_e32 v115, v121
	v_exp_f32_e32 v117, v109
	v_exp_f32_e32 v120, v111
	v_add_f32_e32 v111, 1.0, v119
	v_add_f32_e32 v109, 1.0, v115
	v_add_f32_e32 v115, 1.0, v117
	v_exp_f32_e32 v117, v110
	v_add_f32_e32 v110, 1.0, v118
	v_rcp_f32_e32 v108, v108
	v_add_f32_e32 v114, 1.0, v114
	v_rcp_f32_e32 v109, v109
	v_rcp_f32_e32 v110, v110
	v_add_f32_e32 v117, 1.0, v117
	v_rcp_f32_e32 v111, v111
	v_rcp_f32_e32 v114, v114
	v_rcp_f32_e32 v115, v115
	v_rcp_f32_e32 v118, v117
	v_add_f32_e32 v117, 1.0, v120
	v_rcp_f32_e32 v119, v117
	v_pk_mul_f32 v[96:97], v[100:101], v[96:97]
	v_pk_mul_f32 v[98:99], v[116:117], v[98:99] op_sel_hi:[0,1]
	v_pk_mul_f32 v[96:97], v[116:117], v[96:97] op_sel_hi:[0,1]
	v_lshl_add_u64 v[112:113], s[38:39], 0, v[138:139]
	v_pk_mul_f32 v[100:101], v[116:117], v[104:105] op_sel_hi:[0,1]
	v_pk_mul_f32 v[98:99], v[110:111], v[98:99]
	v_pk_mul_f32 v[96:97], v[108:109], v[96:97]
	v_lshl_add_u64 v[112:113], v[112:113], 0, v[208:209]
	v_pk_mul_f32 v[102:103], v[116:117], v[106:107] op_sel_hi:[0,1]
	v_pk_mul_f32 v[100:101], v[114:115], v[100:101]
	v_cvt_pk_bf16_f32 v96, v96, v97
	v_cvt_pk_bf16_f32 v97, v98, v99
	v_pk_mul_f32 v[102:103], v[118:119], v[102:103]
	v_cvt_pk_bf16_f32 v98, v100, v101
	v_pk_mul_f32 v[88:89], v[92:93], v[88:89]
	v_cvt_pk_bf16_f32 v99, v102, v103
	global_store_dwordx4 v[112:113], v[96:99], off sc1 nt
	v_pk_mul_f32 v[90:91], v[94:95], v[90:91]
	v_mul_f32_e32 v100, v166, v166
	v_mul_f32_e32 v98, 0xbfb8aa3b, v166
	v_pk_mul_f32 v[104:105], v[98:99], v[84:85] op_sel_hi:[0,1]
	v_pk_mul_f32 v[102:103], v[98:99], v[86:87] op_sel_hi:[0,1]
	v_exp_f32_e32 v99, v104
	v_exp_f32_e32 v102, v102
	v_exp_f32_e32 v103, v103
	v_pk_mul_f32 v[82:83], v[86:87], v[82:83]
	v_pk_mul_f32 v[92:93], v[98:99], v[92:93] op_sel_hi:[0,1]
	v_pk_mul_f32 v[94:95], v[98:99], v[94:95] op_sel_hi:[0,1]
	v_exp_f32_e32 v98, v92
	v_add_f32_e32 v92, 1.0, v99
	v_exp_f32_e32 v99, v105
	v_exp_f32_e32 v101, v93
	v_exp_f32_e32 v104, v95
	v_add_f32_e32 v95, 1.0, v103
	v_add_f32_e32 v93, 1.0, v99
	v_add_f32_e32 v99, 1.0, v101
	v_exp_f32_e32 v101, v94
	v_add_f32_e32 v94, 1.0, v102
	v_rcp_f32_e32 v92, v92
	v_add_f32_e32 v98, 1.0, v98
	v_rcp_f32_e32 v93, v93
	v_rcp_f32_e32 v94, v94
	v_add_f32_e32 v101, 1.0, v101
	v_rcp_f32_e32 v95, v95
	v_rcp_f32_e32 v98, v98
	v_rcp_f32_e32 v99, v99
	v_rcp_f32_e32 v102, v101
	v_add_f32_e32 v101, 1.0, v104
	v_rcp_f32_e32 v103, v101
	v_pk_mul_f32 v[80:81], v[84:85], v[80:81]
	v_pk_mul_f32 v[82:83], v[100:101], v[82:83] op_sel_hi:[0,1]
	v_pk_mul_f32 v[80:81], v[100:101], v[80:81] op_sel_hi:[0,1]
	v_lshl_add_u64 v[96:97], s[38:39], 0, v[140:141]
	v_pk_mul_f32 v[84:85], v[100:101], v[88:89] op_sel_hi:[0,1]
	v_pk_mul_f32 v[82:83], v[94:95], v[82:83]
	v_pk_mul_f32 v[80:81], v[92:93], v[80:81]
	v_lshl_add_u64 v[96:97], v[96:97], 0, v[208:209]
	v_pk_mul_f32 v[86:87], v[100:101], v[90:91] op_sel_hi:[0,1]
	v_pk_mul_f32 v[84:85], v[98:99], v[84:85]
	v_cvt_pk_bf16_f32 v80, v80, v81
	v_cvt_pk_bf16_f32 v81, v82, v83
	v_pk_mul_f32 v[86:87], v[102:103], v[86:87]
	v_cvt_pk_bf16_f32 v82, v84, v85
	v_pk_mul_f32 v[72:73], v[76:77], v[72:73]
	v_cvt_pk_bf16_f32 v83, v86, v87
	global_store_dwordx4 v[96:97], v[80:83], off sc1 nt
	v_pk_mul_f32 v[74:75], v[78:79], v[74:75]
	v_mul_f32_e32 v84, v165, v165
	v_mul_f32_e32 v82, 0xbfb8aa3b, v165
	v_pk_mul_f32 v[88:89], v[82:83], v[68:69] op_sel_hi:[0,1]
	v_pk_mul_f32 v[86:87], v[82:83], v[70:71] op_sel_hi:[0,1]
	v_exp_f32_e32 v83, v88
	v_exp_f32_e32 v86, v86
	v_exp_f32_e32 v87, v87
	v_pk_mul_f32 v[66:67], v[70:71], v[66:67]
	v_pk_mul_f32 v[76:77], v[82:83], v[76:77] op_sel_hi:[0,1]
	v_pk_mul_f32 v[78:79], v[82:83], v[78:79] op_sel_hi:[0,1]
	v_exp_f32_e32 v82, v76
	v_add_f32_e32 v76, 1.0, v83
	v_exp_f32_e32 v83, v89
	v_exp_f32_e32 v85, v77
	v_exp_f32_e32 v88, v79
	v_add_f32_e32 v79, 1.0, v87
	v_add_f32_e32 v77, 1.0, v83
	v_add_f32_e32 v83, 1.0, v85
	v_exp_f32_e32 v85, v78
	v_add_f32_e32 v78, 1.0, v86
	v_rcp_f32_e32 v76, v76
	v_add_f32_e32 v82, 1.0, v82
	v_rcp_f32_e32 v77, v77
	v_rcp_f32_e32 v78, v78
	v_add_f32_e32 v85, 1.0, v85
	v_rcp_f32_e32 v79, v79
	v_rcp_f32_e32 v82, v82
	v_rcp_f32_e32 v83, v83
	v_rcp_f32_e32 v86, v85
	v_add_f32_e32 v85, 1.0, v88
	v_rcp_f32_e32 v87, v85
	v_pk_mul_f32 v[64:65], v[68:69], v[64:65]
	v_pk_mul_f32 v[66:67], v[84:85], v[66:67] op_sel_hi:[0,1]
	v_pk_mul_f32 v[64:65], v[84:85], v[64:65] op_sel_hi:[0,1]
	v_lshl_add_u64 v[80:81], s[38:39], 0, v[142:143]
	v_pk_mul_f32 v[68:69], v[84:85], v[72:73] op_sel_hi:[0,1]
	v_pk_mul_f32 v[66:67], v[78:79], v[66:67]
	v_pk_mul_f32 v[64:65], v[76:77], v[64:65]
	v_lshl_add_u64 v[80:81], v[80:81], 0, v[208:209]
	v_pk_mul_f32 v[70:71], v[84:85], v[74:75] op_sel_hi:[0,1]
	v_pk_mul_f32 v[68:69], v[82:83], v[68:69]
	v_cvt_pk_bf16_f32 v64, v64, v65
	v_cvt_pk_bf16_f32 v65, v66, v67
	v_pk_mul_f32 v[70:71], v[86:87], v[70:71]
	v_cvt_pk_bf16_f32 v66, v68, v69
	v_pk_mul_f32 v[56:57], v[60:61], v[56:57]
	v_cvt_pk_bf16_f32 v67, v70, v71
	global_store_dwordx4 v[80:81], v[64:67], off sc1 nt
	v_pk_mul_f32 v[58:59], v[62:63], v[58:59]
	v_mul_f32_e32 v68, v164, v164
	v_mul_f32_e32 v66, 0xbfb8aa3b, v164
	v_pk_mul_f32 v[72:73], v[66:67], v[52:53] op_sel_hi:[0,1]
	v_pk_mul_f32 v[70:71], v[66:67], v[54:55] op_sel_hi:[0,1]
	v_exp_f32_e32 v67, v72
	v_exp_f32_e32 v70, v70
	v_exp_f32_e32 v71, v71
	v_pk_mul_f32 v[50:51], v[54:55], v[50:51]
	v_pk_mul_f32 v[60:61], v[66:67], v[60:61] op_sel_hi:[0,1]
	v_pk_mul_f32 v[62:63], v[66:67], v[62:63] op_sel_hi:[0,1]
	v_exp_f32_e32 v66, v60
	v_add_f32_e32 v60, 1.0, v67
	v_exp_f32_e32 v67, v73
	v_exp_f32_e32 v69, v61
	v_exp_f32_e32 v72, v63
	v_add_f32_e32 v63, 1.0, v71
	v_add_f32_e32 v61, 1.0, v67
	v_add_f32_e32 v67, 1.0, v69
	v_exp_f32_e32 v69, v62
	v_add_f32_e32 v62, 1.0, v70
	v_rcp_f32_e32 v60, v60
	v_add_f32_e32 v66, 1.0, v66
	v_rcp_f32_e32 v61, v61
	v_rcp_f32_e32 v62, v62
	v_add_f32_e32 v69, 1.0, v69
	v_rcp_f32_e32 v63, v63
	v_rcp_f32_e32 v66, v66
	v_rcp_f32_e32 v67, v67
	v_rcp_f32_e32 v70, v69
	v_add_f32_e32 v69, 1.0, v72
	v_rcp_f32_e32 v71, v69
	v_pk_mul_f32 v[48:49], v[52:53], v[48:49]
	v_pk_mul_f32 v[50:51], v[68:69], v[50:51] op_sel_hi:[0,1]
	v_pk_mul_f32 v[48:49], v[68:69], v[48:49] op_sel_hi:[0,1]
	v_lshl_add_u64 v[64:65], s[38:39], 0, v[144:145]
	v_pk_mul_f32 v[52:53], v[68:69], v[56:57] op_sel_hi:[0,1]
	v_pk_mul_f32 v[50:51], v[62:63], v[50:51]
	v_pk_mul_f32 v[48:49], v[60:61], v[48:49]
	v_lshl_add_u64 v[64:65], v[64:65], 0, v[208:209]
	v_pk_mul_f32 v[54:55], v[68:69], v[58:59] op_sel_hi:[0,1]
	v_pk_mul_f32 v[52:53], v[66:67], v[52:53]
	v_cvt_pk_bf16_f32 v48, v48, v49
	v_cvt_pk_bf16_f32 v49, v50, v51
	v_pk_mul_f32 v[54:55], v[70:71], v[54:55]
	v_cvt_pk_bf16_f32 v50, v52, v53
	v_pk_mul_f32 v[40:41], v[44:45], v[40:41]
	v_cvt_pk_bf16_f32 v51, v54, v55
	global_store_dwordx4 v[64:65], v[48:51], off sc1 nt
	v_pk_mul_f32 v[42:43], v[46:47], v[42:43]
	v_mul_f32_e32 v52, v163, v163
	v_mul_f32_e32 v50, 0xbfb8aa3b, v163
	v_pk_mul_f32 v[56:57], v[50:51], v[36:37] op_sel_hi:[0,1]
	v_pk_mul_f32 v[54:55], v[50:51], v[38:39] op_sel_hi:[0,1]
	v_exp_f32_e32 v51, v56
	v_exp_f32_e32 v54, v54
	v_exp_f32_e32 v55, v55
	v_pk_mul_f32 v[34:35], v[38:39], v[34:35]
	v_pk_mul_f32 v[44:45], v[50:51], v[44:45] op_sel_hi:[0,1]
	v_pk_mul_f32 v[46:47], v[50:51], v[46:47] op_sel_hi:[0,1]
	v_exp_f32_e32 v50, v44
	v_add_f32_e32 v44, 1.0, v51
	v_exp_f32_e32 v51, v57
	v_exp_f32_e32 v53, v45
	v_exp_f32_e32 v56, v47
	v_add_f32_e32 v47, 1.0, v55
	v_add_f32_e32 v45, 1.0, v51
	v_add_f32_e32 v51, 1.0, v53
	v_exp_f32_e32 v53, v46
	v_add_f32_e32 v46, 1.0, v54
	v_rcp_f32_e32 v44, v44
	v_add_f32_e32 v50, 1.0, v50
	v_rcp_f32_e32 v45, v45
	v_rcp_f32_e32 v46, v46
	v_add_f32_e32 v53, 1.0, v53
	v_rcp_f32_e32 v47, v47
	v_rcp_f32_e32 v50, v50
	v_rcp_f32_e32 v51, v51
	v_rcp_f32_e32 v54, v53
	v_add_f32_e32 v53, 1.0, v56
	v_rcp_f32_e32 v55, v53
	v_pk_mul_f32 v[32:33], v[36:37], v[32:33]
	v_pk_mul_f32 v[34:35], v[52:53], v[34:35] op_sel_hi:[0,1]
	v_pk_mul_f32 v[32:33], v[52:53], v[32:33] op_sel_hi:[0,1]
	v_lshl_add_u64 v[48:49], s[38:39], 0, v[146:147]
	v_pk_mul_f32 v[36:37], v[52:53], v[40:41] op_sel_hi:[0,1]
	v_pk_mul_f32 v[34:35], v[46:47], v[34:35]
	v_pk_mul_f32 v[32:33], v[44:45], v[32:33]
	v_lshl_add_u64 v[48:49], v[48:49], 0, v[208:209]
	v_pk_mul_f32 v[38:39], v[52:53], v[42:43] op_sel_hi:[0,1]
	v_pk_mul_f32 v[36:37], v[50:51], v[36:37]
	v_cvt_pk_bf16_f32 v32, v32, v33
	v_cvt_pk_bf16_f32 v33, v34, v35
	v_pk_mul_f32 v[38:39], v[54:55], v[38:39]
	v_cvt_pk_bf16_f32 v34, v36, v37
	v_pk_mul_f32 v[24:25], v[28:29], v[24:25]
	v_cvt_pk_bf16_f32 v35, v38, v39
	global_store_dwordx4 v[48:49], v[32:35], off sc1 nt
	v_pk_mul_f32 v[26:27], v[30:31], v[26:27]
	v_mul_f32_e32 v36, v162, v162
	v_mul_f32_e32 v34, 0xbfb8aa3b, v162
	v_pk_mul_f32 v[40:41], v[34:35], v[20:21] op_sel_hi:[0,1]
	v_pk_mul_f32 v[38:39], v[34:35], v[22:23] op_sel_hi:[0,1]
	v_exp_f32_e32 v35, v40
	v_exp_f32_e32 v38, v38
	v_exp_f32_e32 v39, v39
	v_pk_mul_f32 v[18:19], v[22:23], v[18:19]
	v_pk_mul_f32 v[28:29], v[34:35], v[28:29] op_sel_hi:[0,1]
	v_pk_mul_f32 v[30:31], v[34:35], v[30:31] op_sel_hi:[0,1]
	v_exp_f32_e32 v34, v28
	v_add_f32_e32 v28, 1.0, v35
	v_exp_f32_e32 v35, v41
	v_exp_f32_e32 v37, v29
	v_exp_f32_e32 v40, v31
	v_add_f32_e32 v31, 1.0, v39
	v_add_f32_e32 v29, 1.0, v35
	v_add_f32_e32 v35, 1.0, v37
	v_exp_f32_e32 v37, v30
	v_add_f32_e32 v30, 1.0, v38
	v_rcp_f32_e32 v28, v28
	v_add_f32_e32 v34, 1.0, v34
	v_rcp_f32_e32 v29, v29
	v_rcp_f32_e32 v30, v30
	v_add_f32_e32 v37, 1.0, v37
	v_rcp_f32_e32 v31, v31
	v_rcp_f32_e32 v34, v34
	v_rcp_f32_e32 v35, v35
	v_rcp_f32_e32 v38, v37
	v_add_f32_e32 v37, 1.0, v40
	v_rcp_f32_e32 v39, v37
	v_pk_mul_f32 v[16:17], v[20:21], v[16:17]
	v_pk_mul_f32 v[18:19], v[36:37], v[18:19] op_sel_hi:[0,1]
	v_pk_mul_f32 v[16:17], v[36:37], v[16:17] op_sel_hi:[0,1]
	v_lshl_add_u64 v[32:33], s[38:39], 0, v[148:149]
	v_pk_mul_f32 v[20:21], v[36:37], v[24:25] op_sel_hi:[0,1]
	v_pk_mul_f32 v[18:19], v[30:31], v[18:19]
	v_pk_mul_f32 v[16:17], v[28:29], v[16:17]
	v_lshl_add_u64 v[32:33], v[32:33], 0, v[208:209]
	v_pk_mul_f32 v[22:23], v[36:37], v[26:27] op_sel_hi:[0,1]
	v_pk_mul_f32 v[20:21], v[34:35], v[20:21]
	v_cvt_pk_bf16_f32 v16, v16, v17
	v_cvt_pk_bf16_f32 v17, v18, v19
	v_pk_mul_f32 v[22:23], v[38:39], v[22:23]
	v_cvt_pk_bf16_f32 v18, v20, v21
	v_pk_mul_f32 v[8:9], v[12:13], v[8:9]
	v_cvt_pk_bf16_f32 v19, v22, v23
	global_store_dwordx4 v[32:33], v[16:19], off sc1 nt
	v_pk_mul_f32 v[10:11], v[14:15], v[10:11]
	v_mul_f32_e32 v20, v161, v161
	v_mul_f32_e32 v18, 0xbfb8aa3b, v161
	v_pk_mul_f32 v[24:25], v[18:19], v[4:5] op_sel_hi:[0,1]
	v_pk_mul_f32 v[22:23], v[18:19], v[6:7] op_sel_hi:[0,1]
	v_exp_f32_e32 v19, v24
	v_exp_f32_e32 v22, v22
	v_exp_f32_e32 v23, v23
	v_pk_mul_f32 v[2:3], v[6:7], v[2:3]
	v_pk_mul_f32 v[12:13], v[18:19], v[12:13] op_sel_hi:[0,1]
	v_pk_mul_f32 v[14:15], v[18:19], v[14:15] op_sel_hi:[0,1]
	v_exp_f32_e32 v18, v12
	v_add_f32_e32 v12, 1.0, v19
	v_exp_f32_e32 v19, v25
	v_exp_f32_e32 v21, v13
	v_exp_f32_e32 v24, v15
	v_add_f32_e32 v15, 1.0, v23
	v_add_f32_e32 v13, 1.0, v19
	v_add_f32_e32 v19, 1.0, v21
	v_exp_f32_e32 v21, v14
	v_add_f32_e32 v14, 1.0, v22
	v_rcp_f32_e32 v12, v12
	v_add_f32_e32 v18, 1.0, v18
	v_add_f32_e32 v21, 1.0, v21
	v_rcp_f32_e32 v13, v13
	v_rcp_f32_e32 v14, v14
	v_rcp_f32_e32 v22, v21
	v_rcp_f32_e32 v15, v15
	v_add_f32_e32 v21, 1.0, v24
	v_rcp_f32_e32 v18, v18
	v_rcp_f32_e32 v19, v19
	v_rcp_f32_e32 v23, v21
	v_pk_mul_f32 v[0:1], v[4:5], v[0:1]
	v_lshl_add_u64 v[16:17], s[38:39], 0, v[150:151]
	v_pk_mul_f32 v[0:1], v[20:21], v[0:1] op_sel_hi:[0,1]
	v_pk_mul_f32 v[2:3], v[20:21], v[2:3] op_sel_hi:[0,1]
	v_lshl_add_u64 v[16:17], v[16:17], 0, v[208:209]
	v_pk_mul_f32 v[4:5], v[20:21], v[8:9] op_sel_hi:[0,1]
	v_pk_mul_f32 v[6:7], v[20:21], v[10:11] op_sel_hi:[0,1]
	v_pk_mul_f32 v[2:3], v[14:15], v[2:3]
	v_pk_mul_f32 v[0:1], v[12:13], v[0:1]
	s_andn2_b64 vcc, exec, s[36:37]
	s_mov_b64 s[2:3], -1
	v_pk_mul_f32 v[6:7], v[22:23], v[6:7]
	v_pk_mul_f32 v[4:5], v[18:19], v[4:5]
	v_cvt_pk_bf16_f32 v0, v0, v1
	v_cvt_pk_bf16_f32 v1, v2, v3
	s_nop 0
	v_cvt_pk_bf16_f32 v2, v4, v5
	v_cvt_pk_bf16_f32 v3, v6, v7
	global_store_dwordx4 v[16:17], v[0:3], off sc1 nt
	s_cmp_eq_u64 s[24:25], 0
	s_cbranch_scc1 .Lgu_lhalf_done
	s_barrier
